# v112 + leader path no longer posts the unused per-XCD release word
# baseline (speedup 1.0000x reference)
; __device__ __forceinline__ unsigned xb_add(unsigned* p, unsigned v) { return __hip_atomic_fetch_add(p, v, __ATOMIC_RELAXED, __HIP_MEMORY_SCOPE_AGENT); }
; __device__ __forceinline__ void xcd_barrier(const XcdBarrier& b) {
;     ...
;             __builtin_amdgcn_fence(__ATOMIC_ACQUIRE, "agent");
;             xb_add(&bar[XB_XGEN(b.x)], 1u);
;             asm volatile("s_waitcnt vmcnt(0)" ::: "memory");
.LBB0_63:
	s_or_b64 exec, exec, s[4:5]
	v_mov_b32_e32 v0, 0x2000
	s_waitcnt vmcnt(0)
	buffer_inv sc1
	s_waitcnt vmcnt(0)
